# phase_pooled inner loop: the eight loads of an unrolled trip issued together at the top (one wait per 4 tokens)
# speedup vs baseline: 1.0088x; 1.0088x over previous
; DI float bflo(unsigned v) { return __uint_as_float(v << 16); }
; DI float bfhi(unsigned v) { return __uint_as_float(v & 0xffff0000u); }
; DI void phase_pooled(const Params& P) {
;     ...
; #pragma unroll 4
;     for (int i = 0; i < 16; ++i) {
;       const i32x4 v = *(const i32x4*)(base + (size_t)i * 512);
;       float x0[8];
; #pragma unroll
;       for (int e = 0; e < 4; ++e) {
;         x0[2 * e] = bflo((unsigned)v[e]); x0[2 * e + 1] = bfhi((unsigned)v[e]);
;         run[2 * e] += x0[2 * e]; run[2 * e + 1] += x0[2 * e + 1];
;       }
;       const int s = s0 + i;
;       const float inv = 1.f / (float)min(s + 1, win);
;       i32x4 o;
; #pragma unroll
;       for (int e = 0; e < 4; ++e) o[e] = (int)pack2(run[2 * e] * inv - x0[2 * e], run[2 * e + 1] * inv - x0[2 * e + 1]);
;       *(i32x4*)(pooled + (size_t)(t0 + i) * 512 + c8 * 8) = o;
;       if (s - win + 1 >= 0) {
;         const i32x4 w = *(const i32x4*)(base + (size_t)(i - win + 1) * 512);
; #pragma unroll
;         for (int e = 0; e < 4; ++e) { run[2 * e] -= bflo((unsigned)w[e]); run[2 * e + 1] -= bfhi((unsigned)w[e]); }
;       }
;     }
.LBB0_793:
	v_lshl_add_u64 v[10:11], v[6:7], 0, s[8:9]
	v_add_co_u32_e32 v78, vcc, 0x1d000000, v10
	s_nop 1
	v_addc_co_u32_e32 v79, vcc, 0, v11, vcc
	global_load_dwordx4 v[44:47], v[78:79], off
	global_load_dwordx4 v[48:51], v[78:79], off offset:1024
	global_load_dwordx4 v[52:55], v[78:79], off offset:2048
	global_load_dwordx4 v[56:59], v[78:79], off offset:3072
	v_lshl_add_u64 v[76:77], v[8:9], 0, s[8:9]
	v_add_co_u32_e32 v76, vcc, 0x1d001000, v76
	s_nop 1
	v_addc_co_u32_e32 v77, vcc, 0, v77, vcc
	global_load_dwordx4 v[60:63], v[76:77], off offset:-3072
	global_load_dwordx4 v[64:67], v[76:77], off offset:-2048
	global_load_dwordx4 v[68:71], v[76:77], off offset:-1024
	global_load_dwordx4 v[72:75], v[76:77], off
	s_waitcnt vmcnt(0)
	v_add_co_u32_e32 v12, vcc, 0x1d000000, v10
	s_nop 1
	v_addc_co_u32_e32 v13, vcc, 0, v11, vcc
	v_mov_b32_e32 v30, v44
	v_mov_b32_e32 v31, v45
	v_mov_b32_e32 v32, v46
	v_mov_b32_e32 v33, v47
	v_lshlrev_b32_e32 v12, 16, v30
	v_and_b32_e32 v13, 0xffff0000, v30
	v_lshlrev_b32_e32 v34, 16, v32
	v_and_b32_e32 v35, 0xffff0000, v32
	v_lshlrev_b32_e32 v36, 16, v33
	v_and_b32_e32 v37, 0xffff0000, v33
	v_add_u32_e32 v30, 1, v29
	v_pk_add_f32 v[22:23], v[14:15], v[12:13]
	v_pk_add_f32 v[14:15], v[18:19], v[34:35]
	v_pk_add_f32 v[18:19], v[20:21], v[36:37]
	v_min_i32_e32 v20, v30, v27
	v_cvt_f32_u32_e32 v20, v20
	v_lshlrev_b32_e32 v24, 16, v31
	v_and_b32_e32 v25, 0xffff0000, v31
	v_pk_add_f32 v[16:17], v[16:17], v[24:25]
	v_div_scale_f32 v21, s[10:11], v20, v20, 1.0
	v_rcp_f32_e32 v31, v21
	s_nop 0
	v_fma_f32 v32, -v21, v31, 1.0
	v_fmac_f32_e32 v31, v32, v31
	v_div_scale_f32 v32, vcc, 1.0, v20, 1.0
	v_mul_f32_e32 v33, v32, v31
	v_fma_f32 v38, -v21, v33, v32
	v_fmac_f32_e32 v33, v38, v31
	v_fma_f32 v21, -v21, v33, v32
	v_div_fmas_f32 v21, v21, v31, v33
	v_div_fixup_f32 v20, v21, v20, 1.0
	v_pk_fma_f32 v[12:13], v[20:21], v[22:23], v[12:13] op_sel_hi:[0,1,1] neg_lo:[0,0,1] neg_hi:[0,0,1]
	v_cvt_pk_bf16_f32 v32, v12, v13
	v_pk_fma_f32 v[12:13], v[20:21], v[16:17], v[24:25] op_sel_hi:[0,1,1] neg_lo:[0,0,1] neg_hi:[0,0,1]
	v_cvt_pk_bf16_f32 v33, v12, v13
	v_pk_fma_f32 v[12:13], v[20:21], v[14:15], v[34:35] op_sel_hi:[0,1,1] neg_lo:[0,0,1] neg_hi:[0,0,1]
	v_cvt_pk_bf16_f32 v34, v12, v13
	v_pk_fma_f32 v[12:13], v[20:21], v[18:19], v[36:37] op_sel_hi:[0,1,1] neg_lo:[0,0,1] neg_hi:[0,0,1]
	v_cvt_pk_bf16_f32 v35, v12, v13
	v_add_co_u32_e32 v12, vcc, 0xf000000, v10
	s_nop 1
	v_addc_co_u32_e32 v13, vcc, 0, v11, vcc
	global_store_dwordx4 v[12:13], v[32:35], off
	v_cmp_ge_u32_e32 vcc, v29, v27
	v_lshl_add_u64 v[12:13], v[8:9], 0, s[8:9]
	s_and_saveexec_b64 s[10:11], vcc
	s_cbranch_execz .LBB0_795
	v_add_co_u32_e32 v20, vcc, 0x1d000000, v12
	s_nop 1
	v_addc_co_u32_e32 v21, vcc, 0, v13, vcc
	v_mov_b32_e32 v32, v60
	v_mov_b32_e32 v33, v61
	v_mov_b32_e32 v34, v62
	v_mov_b32_e32 v35, v63
	v_lshlrev_b32_e32 v20, 16, v32
	v_and_b32_e32 v21, 0xffff0000, v32
	v_pk_add_f32 v[22:23], v[22:23], v[20:21] neg_lo:[0,1] neg_hi:[0,1]
	v_lshlrev_b32_e32 v20, 16, v33
	v_and_b32_e32 v21, 0xffff0000, v33
	v_pk_add_f32 v[16:17], v[16:17], v[20:21] neg_lo:[0,1] neg_hi:[0,1]
	v_lshlrev_b32_e32 v20, 16, v34
	v_and_b32_e32 v21, 0xffff0000, v34
	v_pk_add_f32 v[14:15], v[14:15], v[20:21] neg_lo:[0,1] neg_hi:[0,1]
	v_lshlrev_b32_e32 v20, 16, v35
	v_and_b32_e32 v21, 0xffff0000, v35
	v_pk_add_f32 v[18:19], v[18:19], v[20:21] neg_lo:[0,1] neg_hi:[0,1]
.LBB0_795:
	s_or_b64 exec, exec, s[10:11]
	v_add_co_u32_e32 v20, vcc, 0x1d000000, v10
	v_add_u32_e32 v31, 2, v29
	s_nop 0
	v_addc_co_u32_e32 v21, vcc, 0, v11, vcc
	v_mov_b32_e32 v32, v48
	v_mov_b32_e32 v33, v49
	v_mov_b32_e32 v34, v50
	v_mov_b32_e32 v35, v51
	v_lshlrev_b32_e32 v40, 16, v34
	v_and_b32_e32 v41, 0xffff0000, v34
	v_pk_add_f32 v[20:21], v[14:15], v[40:41]
	v_lshlrev_b32_e32 v14, 16, v35
	v_and_b32_e32 v15, 0xffff0000, v35
	v_pk_add_f32 v[24:25], v[18:19], v[14:15]
	v_min_i32_e32 v18, v31, v27
	v_cvt_f32_u32_e32 v18, v18
	v_lshlrev_b32_e32 v36, 16, v32
	v_and_b32_e32 v37, 0xffff0000, v32
	v_lshlrev_b32_e32 v38, 16, v33
	v_div_scale_f32 v19, s[10:11], v18, v18, 1.0
	v_rcp_f32_e32 v32, v19
	v_and_b32_e32 v39, 0xffff0000, v33
	v_pk_add_f32 v[22:23], v[22:23], v[36:37]
	v_pk_add_f32 v[16:17], v[16:17], v[38:39]
	v_fma_f32 v33, -v19, v32, 1.0
	v_fmac_f32_e32 v32, v33, v32
	v_div_scale_f32 v33, vcc, 1.0, v18, 1.0
	v_mul_f32_e32 v34, v33, v32
	v_fma_f32 v35, -v19, v34, v33
	v_fmac_f32_e32 v34, v35, v32
	v_fma_f32 v19, -v19, v34, v33
	v_div_fmas_f32 v19, v19, v32, v34
	v_div_fixup_f32 v18, v19, v18, 1.0
	v_pk_fma_f32 v[32:33], v[18:19], v[22:23], v[36:37] op_sel_hi:[0,1,1] neg_lo:[0,0,1] neg_hi:[0,0,1]
	v_pk_fma_f32 v[34:35], v[18:19], v[16:17], v[38:39] op_sel_hi:[0,1,1] neg_lo:[0,0,1] neg_hi:[0,0,1]
	v_cvt_pk_bf16_f32 v32, v32, v33
	v_cvt_pk_bf16_f32 v33, v34, v35
	v_pk_fma_f32 v[34:35], v[18:19], v[20:21], v[40:41] op_sel_hi:[0,1,1] neg_lo:[0,0,1] neg_hi:[0,0,1]
	v_pk_fma_f32 v[14:15], v[18:19], v[24:25], v[14:15] op_sel_hi:[0,1,1] neg_lo:[0,0,1] neg_hi:[0,0,1]
	v_cvt_pk_bf16_f32 v34, v34, v35
	v_cvt_pk_bf16_f32 v35, v14, v15
	v_add_co_u32_e32 v14, vcc, 0xf000000, v10
	s_nop 1
	v_addc_co_u32_e32 v15, vcc, 0, v11, vcc
	v_cmp_gt_i32_e32 vcc, v30, v28
	global_store_dwordx4 v[14:15], v[32:35], off offset:1024
	s_and_saveexec_b64 s[10:11], vcc
	s_cbranch_execz .LBB0_797
	v_add_co_u32_e32 v14, vcc, 0x1d000000, v12
	s_nop 1
	v_addc_co_u32_e32 v15, vcc, 0, v13, vcc
	v_mov_b32_e32 v32, v64
	v_mov_b32_e32 v33, v65
	v_mov_b32_e32 v34, v66
	v_mov_b32_e32 v35, v67
	v_lshlrev_b32_e32 v14, 16, v32
	v_and_b32_e32 v15, 0xffff0000, v32
	v_pk_add_f32 v[22:23], v[22:23], v[14:15] neg_lo:[0,1] neg_hi:[0,1]
	v_lshlrev_b32_e32 v14, 16, v33
	v_and_b32_e32 v15, 0xffff0000, v33
	v_pk_add_f32 v[16:17], v[16:17], v[14:15] neg_lo:[0,1] neg_hi:[0,1]
	v_lshlrev_b32_e32 v14, 16, v34
	v_and_b32_e32 v15, 0xffff0000, v34
	v_pk_add_f32 v[20:21], v[20:21], v[14:15] neg_lo:[0,1] neg_hi:[0,1]
	v_lshlrev_b32_e32 v14, 16, v35
	v_and_b32_e32 v15, 0xffff0000, v35
	v_pk_add_f32 v[24:25], v[24:25], v[14:15] neg_lo:[0,1] neg_hi:[0,1]
; DI float bflo(unsigned v) { return __uint_as_float(v << 16); }
; DI float bfhi(unsigned v) { return __uint_as_float(v & 0xffff0000u); }
; DI void phase_pooled(const Params& P) {
;     ...
; #pragma unroll 4
;     for (int i = 0; i < 16; ++i) {
;       const i32x4 v = *(const i32x4*)(base + (size_t)i * 512);
;       float x0[8];
; #pragma unroll
;       for (int e = 0; e < 4; ++e) {
;         x0[2 * e] = bflo((unsigned)v[e]); x0[2 * e + 1] = bfhi((unsigned)v[e]);
;         run[2 * e] += x0[2 * e]; run[2 * e + 1] += x0[2 * e + 1];
;       }
;       const int s = s0 + i;
;       const float inv = 1.f / (float)min(s + 1, win);
;       i32x4 o;
; #pragma unroll
;       for (int e = 0; e < 4; ++e) o[e] = (int)pack2(run[2 * e] * inv - x0[2 * e], run[2 * e + 1] * inv - x0[2 * e + 1]);
;       *(i32x4*)(pooled + (size_t)(t0 + i) * 512 + c8 * 8) = o;
;       if (s - win + 1 >= 0) {
;         const i32x4 w = *(const i32x4*)(base + (size_t)(i - win + 1) * 512);
; #pragma unroll
;         for (int e = 0; e < 4; ++e) { run[2 * e] -= bflo((unsigned)w[e]); run[2 * e + 1] -= bfhi((unsigned)w[e]); }
;       }
;     }
.LBB0_797:
	s_or_b64 exec, exec, s[10:11]
	v_add_co_u32_e32 v14, vcc, 0x1d000000, v10
	s_nop 1
	v_addc_co_u32_e32 v15, vcc, 0, v11, vcc
	v_mov_b32_e32 v32, v52
	v_mov_b32_e32 v33, v53
	v_mov_b32_e32 v34, v54
	v_mov_b32_e32 v35, v55
	v_lshlrev_b32_e32 v36, 16, v32
	v_and_b32_e32 v37, 0xffff0000, v32
	v_pk_add_f32 v[14:15], v[22:23], v[36:37]
	v_add_u32_e32 v22, 3, v29
	v_min_i32_e32 v23, v22, v27
	v_cvt_f32_u32_e32 v23, v23
	v_lshlrev_b32_e32 v40, 16, v34
	v_and_b32_e32 v41, 0xffff0000, v34
	v_lshlrev_b32_e32 v42, 16, v35
	v_and_b32_e32 v43, 0xffff0000, v35
	v_pk_add_f32 v[18:19], v[20:21], v[40:41]
	v_pk_add_f32 v[20:21], v[24:25], v[42:43]
	v_div_scale_f32 v24, s[10:11], v23, v23, 1.0
	v_rcp_f32_e32 v25, v24
	v_lshlrev_b32_e32 v38, 16, v33
	v_and_b32_e32 v39, 0xffff0000, v33
	v_pk_add_f32 v[16:17], v[16:17], v[38:39]
	v_fma_f32 v30, -v24, v25, 1.0
	v_fmac_f32_e32 v25, v30, v25
	v_div_scale_f32 v30, vcc, 1.0, v23, 1.0
	v_mul_f32_e32 v32, v30, v25
	v_fma_f32 v33, -v24, v32, v30
	v_fmac_f32_e32 v32, v33, v25
	v_fma_f32 v24, -v24, v32, v30
	v_div_fmas_f32 v24, v24, v25, v32
	v_div_fixup_f32 v24, v24, v23, 1.0
	v_pk_fma_f32 v[32:33], v[24:25], v[14:15], v[36:37] op_sel_hi:[0,1,1] neg_lo:[0,0,1] neg_hi:[0,0,1]
	v_pk_fma_f32 v[34:35], v[24:25], v[16:17], v[38:39] op_sel_hi:[0,1,1] neg_lo:[0,0,1] neg_hi:[0,0,1]
	v_cvt_pk_bf16_f32 v32, v32, v33
	v_cvt_pk_bf16_f32 v33, v34, v35
	v_pk_fma_f32 v[34:35], v[24:25], v[18:19], v[40:41] op_sel_hi:[0,1,1] neg_lo:[0,0,1] neg_hi:[0,0,1]
	v_pk_fma_f32 v[24:25], v[24:25], v[20:21], v[42:43] op_sel_hi:[0,1,1] neg_lo:[0,0,1] neg_hi:[0,0,1]
	v_cvt_pk_bf16_f32 v34, v34, v35
	v_cvt_pk_bf16_f32 v35, v24, v25
	v_add_co_u32_e32 v24, vcc, 0xf000000, v10
	s_nop 1
	v_addc_co_u32_e32 v25, vcc, 0, v11, vcc
	v_cmp_ge_u32_e32 vcc, v31, v27
	global_store_dwordx4 v[24:25], v[32:35], off offset:2048
	s_and_saveexec_b64 s[10:11], vcc
	s_cbranch_execz .LBB0_799
	v_add_co_u32_e32 v24, vcc, 0x1d000000, v12
	s_nop 1
	v_addc_co_u32_e32 v25, vcc, 0, v13, vcc
	v_mov_b32_e32 v30, v68
	v_mov_b32_e32 v31, v69
	v_mov_b32_e32 v32, v70
	v_mov_b32_e32 v33, v71
	v_lshlrev_b32_e32 v24, 16, v30
	v_and_b32_e32 v25, 0xffff0000, v30
	v_pk_add_f32 v[14:15], v[14:15], v[24:25] neg_lo:[0,1] neg_hi:[0,1]
	v_lshlrev_b32_e32 v24, 16, v31
	v_and_b32_e32 v25, 0xffff0000, v31
	v_pk_add_f32 v[16:17], v[16:17], v[24:25] neg_lo:[0,1] neg_hi:[0,1]
	v_lshlrev_b32_e32 v24, 16, v32
	v_and_b32_e32 v25, 0xffff0000, v32
	v_pk_add_f32 v[18:19], v[18:19], v[24:25] neg_lo:[0,1] neg_hi:[0,1]
	v_lshlrev_b32_e32 v24, 16, v33
	v_and_b32_e32 v25, 0xffff0000, v33
	v_pk_add_f32 v[20:21], v[20:21], v[24:25] neg_lo:[0,1] neg_hi:[0,1]
.LBB0_799:
	s_or_b64 exec, exec, s[10:11]
	v_add_co_u32_e32 v24, vcc, 0x1d000000, v10
	v_add_u32_e32 v29, 4, v29
	s_nop 0
	v_addc_co_u32_e32 v25, vcc, 0, v11, vcc
	v_mov_b32_e32 v30, v56
	v_mov_b32_e32 v31, v57
	v_mov_b32_e32 v32, v58
	v_mov_b32_e32 v33, v59
	v_min_i32_e32 v23, v29, v27
	v_cvt_f32_u32_e32 v23, v23
	v_lshlrev_b32_e32 v24, 16, v30
	v_and_b32_e32 v25, 0xffff0000, v30
	v_div_scale_f32 v30, s[10:11], v23, v23, 1.0
	v_lshlrev_b32_e32 v34, 16, v31
	v_and_b32_e32 v35, 0xffff0000, v31
	v_rcp_f32_e32 v31, v30
	v_lshlrev_b32_e32 v36, 16, v32
	v_and_b32_e32 v37, 0xffff0000, v32
	v_lshlrev_b32_e32 v38, 16, v33
	v_fma_f32 v32, -v30, v31, 1.0
	v_fmac_f32_e32 v31, v32, v31
	v_div_scale_f32 v32, vcc, 1.0, v23, 1.0
	v_and_b32_e32 v39, 0xffff0000, v33
	v_mul_f32_e32 v33, v32, v31
	v_fma_f32 v40, -v30, v33, v32
	v_fmac_f32_e32 v33, v40, v31
	v_fma_f32 v30, -v30, v33, v32
	v_div_fmas_f32 v30, v30, v31, v33
	v_pk_add_f32 v[14:15], v[14:15], v[24:25]
	v_div_fixup_f32 v40, v30, v23, 1.0
	v_pk_add_f32 v[16:17], v[16:17], v[34:35]
	v_pk_fma_f32 v[24:25], v[40:41], v[14:15], v[24:25] op_sel_hi:[0,1,1] neg_lo:[0,0,1] neg_hi:[0,0,1]
	v_pk_add_f32 v[18:19], v[18:19], v[36:37]
	v_cvt_pk_bf16_f32 v30, v24, v25
	v_pk_fma_f32 v[24:25], v[40:41], v[16:17], v[34:35] op_sel_hi:[0,1,1] neg_lo:[0,0,1] neg_hi:[0,0,1]
	v_pk_add_f32 v[20:21], v[20:21], v[38:39]
	v_cvt_pk_bf16_f32 v31, v24, v25
	v_pk_fma_f32 v[24:25], v[40:41], v[18:19], v[36:37] op_sel_hi:[0,1,1] neg_lo:[0,0,1] neg_hi:[0,0,1]
	v_add_co_u32_e32 v10, vcc, 0xf000000, v10
	v_cvt_pk_bf16_f32 v32, v24, v25
	v_pk_fma_f32 v[24:25], v[40:41], v[20:21], v[38:39] op_sel_hi:[0,1,1] neg_lo:[0,0,1] neg_hi:[0,0,1]
	v_addc_co_u32_e32 v11, vcc, 0, v11, vcc
	v_cvt_pk_bf16_f32 v33, v24, v25
	v_cmp_gt_i32_e32 vcc, v22, v28
	global_store_dwordx4 v[10:11], v[30:33], off offset:3072
	s_and_saveexec_b64 s[10:11], vcc
	s_cbranch_execz .LBB0_792
	v_add_co_u32_e32 v10, vcc, 0x1d001000, v12
	s_nop 1
	v_addc_co_u32_e32 v11, vcc, 0, v13, vcc
	v_mov_b32_e32 v10, v72
	v_mov_b32_e32 v11, v73
	v_mov_b32_e32 v12, v74
	v_mov_b32_e32 v13, v75
	v_lshlrev_b32_e32 v22, 16, v10
	v_and_b32_e32 v23, 0xffff0000, v10
	v_lshlrev_b32_e32 v10, 16, v11
	v_and_b32_e32 v11, 0xffff0000, v11
	v_pk_add_f32 v[16:17], v[16:17], v[10:11] neg_lo:[0,1] neg_hi:[0,1]
	v_lshlrev_b32_e32 v10, 16, v12
	v_and_b32_e32 v11, 0xffff0000, v12
	v_pk_add_f32 v[18:19], v[18:19], v[10:11] neg_lo:[0,1] neg_hi:[0,1]
	v_lshlrev_b32_e32 v10, 16, v13
	v_and_b32_e32 v11, 0xffff0000, v13
	v_pk_add_f32 v[14:15], v[14:15], v[22:23] neg_lo:[0,1] neg_hi:[0,1]
	v_pk_add_f32 v[20:21], v[20:21], v[10:11] neg_lo:[0,1] neg_hi:[0,1]
	s_branch .LBB0_792

; template <int MF, int NF, bool SWAP = true>
; DI void gemm_main(f32x4 (&acc)[MF][NF], const u16* __restrict__ Ab, int lda, const u16* __restrict__ Bb, int ldb,
;                   int K, char* shm) {
;     ...
;   int sR0, sC0;
;   stage_rc<2>(wid * 1024 + lane * 16, sR0, sC0);
; #pragma unroll
;   for (int m = 0; m < MF; ++m)
; #pragma unroll
;     for (int n = 0; n < NF; ++n) acc[m][n] = f32x4{0.f, 0.f, 0.f, 0.f};
;   const int nt = K >> 6;
;   const int pa0 = sR0 * lda + sC0, pb0 = sR0 * ldb + sC0;
;     ...
;   const int a_off = lds_byte<2>(fr, fq * 8) + wr * (MF * 2048);
;   const int b_off = lds_byte<2>(fr, fq * 8) + wc * (NF * 2048);
;   G_STAGE(0, 0);
;   if constexpr (RING3) {
;     if (nt > 1) { G_STAGE(1, 1); asm volatile("s_waitcnt vmcnt(6)" ::: "memory"); }
;     else asm volatile("s_waitcnt vmcnt(0)" ::: "memory");
;     asm volatile("s_waitcnt lgkmcnt(0)" ::: "memory");
;     __builtin_amdgcn_s_barrier();
;   } else {
;     asm volatile("s_waitcnt vmcnt(0)" ::: "memory");
;     __syncthreads();
;   }
.LBB0_817:
	s_ashr_i32 s0, s16, 31
	s_lshr_b32 s0, s0, 29
	s_add_i32 s0, s16, s0
	s_ashr_i32 s1, s0, 3
	s_and_b32 s0, s0, -8
	s_sub_i32 s0, s16, s0
	s_lshr_b32 s4, s0, 31
	s_or_b32 s4, s4, 32
	s_mul_i32 s0, s4, s0
	s_add_i32 s0, s0, s1
	s_ashr_i32 s1, s0, 31
	s_lshr_b32 s1, s1, 28
	s_add_i32 s1, s0, s1
	s_ashr_i32 s4, s1, 4
	s_lshl_b32 s4, s4, 3
	s_sub_i32 s5, 0x80, s4
	s_min_u32 s5, s5, 8
	s_and_b32 s1, s1, -16
	s_sub_i32 s6, s0, s1
	v_cvt_f32_ubyte0_e32 v1, s5
	v_cvt_f32_i32_e32 v0, s6
	v_rcp_iflag_f32_e32 v2, v1
	s_ashr_i32 s0, s6, 30
	s_or_b32 s7, s0, 1
	v_mov_b32_e32 v10, v135
	v_mul_f32_e32 v2, v0, v2
	v_trunc_f32_e32 v2, v2
	v_fma_f32 v0, -v2, v1, v0
	v_cvt_i32_f32_e32 v2, v2
	v_cmp_ge_f32_e64 s[0:1], |v0|, v1
	s_and_b64 s[0:1], s[0:1], exec
	s_cselect_b32 s0, s7, 0
	v_readfirstlane_b32 s1, v2
	s_add_i32 s0, s1, s0
	s_sext_i32_i8 s1, s0
	s_mul_i32 s0, s0, s5
	s_sub_i32 s0, s6, s0
	s_sext_i32_i8 s0, s0
	s_add_i32 s4, s4, s0
	s_lshl_b32 s0, s4, 8
	s_lshl_b32 s8, s1, 8
	s_ashr_i32 s1, s0, 31
	s_lshl_b64 s[4:5], s[0:1], 10
	s_add_u32 s1, s10, s4
	v_lshlrev_b32_e32 v0, 4, v10
	v_and_b32_e32 v2, 32, v10
	v_ashrrev_i32_e32 v11, 6, v10
	v_lshrrev_b32_e32 v3, 31, v10
	v_bitop3_b32 v0, v0, v2, 48 bitop3:0x6c
	s_addc_u32 s7, s11, s5
	s_ashr_i32 s9, s8, 31
	v_add_u32_e32 v3, v11, v3
	v_lshrrev_b32_e32 v13, 1, v0
	v_lshlrev_b32_e32 v0, 7, v10
	s_lshl_b64 s[4:5], s[8:9], 1
	v_and_b32_e32 v1, 15, v10
	v_ashrrev_i32_e32 v12, 1, v3
	v_and_b32_e32 v3, 0x7fffffe, v3
	v_and_b32_e32 v14, 0x1e00, v0
	s_add_u32 s6, s1, s4
	v_sub_u32_e32 v3, v11, v3
	v_lshl_or_b32 v0, v12, 13, v14
	v_lshlrev_b32_e32 v15, 6, v1
	v_lshlrev_b32_e32 v1, 2, v10
	s_addc_u32 s7, s7, s5
	s_lshl_b64 s[8:9], s[8:9], 10
	v_lshl_add_u32 v0, v3, 5, v0
	v_and_b32_e32 v16, 32, v1
	v_lshlrev_b32_e32 v1, 6, v10
	s_add_u32 s1, s12, s8
	v_or_b32_e32 v0, v0, v13
	v_and_b32_e32 v130, 0xffffc000, v1
	v_lshlrev_b32_e32 v1, 13, v11
	s_addc_u32 s9, s13, s9
	v_lshlrev_b32_e32 v129, 10, v11
	v_and_b32_e32 v131, 0x6000, v1
	v_ashrrev_i32_e32 v1, 31, v0
	s_add_u32 s8, s1, s4
	v_lshlrev_b64 v[2:3], 1, v[0:1]
	v_readfirstlane_b32 s1, v129
	v_lshl_add_u64 v[4:5], s[6:7], 0, v[2:3]
	s_mov_b32 m0, s1
	s_mov_b64 s[18:19], 0x10000
	v_add_u32_e32 v1, 0x2000, v129
	v_add_u32_e32 v0, 0x10000, v0
	global_load_lds_dwordx4 v[4:5], off
	v_lshl_add_u64 v[4:5], v[2:3], 0, s[18:19]
	v_readfirstlane_b32 s1, v1
	v_ashrrev_i32_e32 v1, 31, v0
	v_add_u32_e32 v8, 0x4000, v129
	v_lshl_add_u64 v[6:7], s[6:7], 0, v[4:5]
	s_mov_b32 m0, s1
	v_lshlrev_b64 v[0:1], 1, v[0:1]
	v_readfirstlane_b32 s1, v8
	global_load_lds_dwordx4 v[6:7], off
	v_lshl_add_u64 v[6:7], s[6:7], 0, v[0:1]
	s_mov_b32 m0, s1
	s_mov_b64 s[18:19], 0x30000
	v_add_u32_e32 v17, 0x6000, v129
	global_load_lds_dwordx4 v[6:7], off
	v_lshl_add_u64 v[6:7], v[2:3], 0, s[18:19]
	v_readfirstlane_b32 s1, v17
	v_lshl_add_u64 v[8:9], s[6:7], 0, v[6:7]
	s_mov_b32 m0, s1
	s_addc_u32 s9, s9, s5
	global_load_lds_dwordx4 v[8:9], off
	v_and_b32_e32 v8, 48, v10
	v_bitop3_b32 v132, v15, v16, v8 bitop3:0x36
	v_add_u32_e32 v8, 0x8000, v129
	v_lshl_add_u64 v[2:3], s[8:9], 0, v[2:3]
	v_readfirstlane_b32 s1, v8
	s_mov_b32 m0, s1
	v_lshl_add_u64 v[0:1], s[8:9], 0, v[0:1]
	global_load_lds_dwordx4 v[2:3], off
	v_lshl_add_u64 v[2:3], s[8:9], 0, v[4:5]
	v_add_u32_e32 v4, 0xa000, v129
	s_mov_b32 s17, 0
	v_readfirstlane_b32 s1, v4
	s_mov_b32 m0, s1
	s_mov_b32 s18, 0
	global_load_lds_dwordx4 v[2:3], off
	v_add_u32_e32 v2, 0xc000, v129
	s_nop 0
	v_readfirstlane_b32 s1, v2
	v_add_u32_e32 v2, 0xe000, v129
	s_mov_b32 m0, s1
	v_readfirstlane_b32 s1, v2
	global_load_lds_dwordx4 v[0:1], off
	v_lshl_add_u64 v[0:1], s[8:9], 0, v[6:7]
	s_mov_b32 m0, s1
	s_movk_i32 s1, 0x1fc0
	global_load_lds_dwordx4 v[0:1], off
	s_waitcnt vmcnt(0)
	v_mul_lo_u32 v0, v12, s1
	v_or_b32_e32 v0, v13, v0
	v_lshlrev_b32_e32 v1, 5, v11
	v_mov_b32_e32 v12, 0
	v_add3_u32 v136, v0, v14, v1
	s_mov_b32 s1, 0
	v_mov_b32_e32 v13, v12
	v_mov_b32_e32 v14, v12
	v_mov_b32_e32 v15, v12
	v_mov_b32_e32 v0, v12
	v_mov_b32_e32 v1, v12
	v_mov_b32_e32 v2, v12
	v_mov_b32_e32 v3, v12
	v_mov_b32_e32 v4, v12
	v_mov_b32_e32 v5, v12
	v_mov_b32_e32 v6, v12
	v_mov_b32_e32 v7, v12
	v_mov_b32_e32 v8, v12
	v_mov_b32_e32 v9, v12
	v_mov_b32_e32 v10, v12
	v_mov_b32_e32 v11, v12
	v_mov_b32_e32 v16, v12
	v_mov_b32_e32 v17, v12
	v_mov_b32_e32 v18, v12
	v_mov_b32_e32 v19, v12
	v_mov_b32_e32 v20, v12
	v_mov_b32_e32 v21, v12
	v_mov_b32_e32 v22, v12
	v_mov_b32_e32 v23, v12
	v_mov_b32_e32 v24, v12
	v_mov_b32_e32 v25, v12
	v_mov_b32_e32 v26, v12
	v_mov_b32_e32 v27, v12
	v_mov_b32_e32 v28, v12
	v_mov_b32_e32 v29, v12
	v_mov_b32_e32 v30, v12
	v_mov_b32_e32 v31, v12
	v_mov_b32_e32 v32, v12
	v_mov_b32_e32 v33, v12
	v_mov_b32_e32 v34, v12
	v_mov_b32_e32 v35, v12
	v_mov_b32_e32 v36, v12
	v_mov_b32_e32 v37, v12
	v_mov_b32_e32 v38, v12
	v_mov_b32_e32 v39, v12
	v_mov_b32_e32 v40, v12
	v_mov_b32_e32 v41, v12
	v_mov_b32_e32 v42, v12
	v_mov_b32_e32 v43, v12
	v_mov_b32_e32 v44, v12
	v_mov_b32_e32 v45, v12
	v_mov_b32_e32 v46, v12
	v_mov_b32_e32 v47, v12
	v_mov_b32_e32 v48, v12
	v_mov_b32_e32 v49, v12
	v_mov_b32_e32 v50, v12
	v_mov_b32_e32 v51, v12
	v_mov_b32_e32 v52, v12
	v_mov_b32_e32 v53, v12
	v_mov_b32_e32 v54, v12
	v_mov_b32_e32 v55, v12
	v_mov_b32_e32 v56, v12
	v_mov_b32_e32 v57, v12
	v_mov_b32_e32 v58, v12
	v_mov_b32_e32 v59, v12
	v_mov_b32_e32 v60, v12
	v_mov_b32_e32 v61, v12
	v_mov_b32_e32 v62, v12
	v_mov_b32_e32 v63, v12
	v_mov_b32_e32 v64, v12
	v_mov_b32_e32 v65, v12
	v_mov_b32_e32 v66, v12
	v_mov_b32_e32 v67, v12
	v_mov_b32_e32 v68, v12
	v_mov_b32_e32 v69, v12
	v_mov_b32_e32 v70, v12
	v_mov_b32_e32 v71, v12
	v_mov_b32_e32 v72, v12
	v_mov_b32_e32 v73, v12
	v_mov_b32_e32 v74, v12
	v_mov_b32_e32 v75, v12
	v_mov_b32_e32 v76, v12
	v_mov_b32_e32 v77, v12
	v_mov_b32_e32 v78, v12
	v_mov_b32_e32 v79, v12
	v_mov_b32_e32 v80, v12
	v_mov_b32_e32 v81, v12
	v_mov_b32_e32 v82, v12
	v_mov_b32_e32 v83, v12
	v_mov_b32_e32 v84, v12
	v_mov_b32_e32 v85, v12
	v_mov_b32_e32 v86, v12
	v_mov_b32_e32 v87, v12
	v_mov_b32_e32 v88, v12
	v_mov_b32_e32 v89, v12
	v_mov_b32_e32 v90, v12
	v_mov_b32_e32 v91, v12
	v_mov_b32_e32 v92, v12
	v_mov_b32_e32 v93, v12
	v_mov_b32_e32 v94, v12
	v_mov_b32_e32 v95, v12
	v_mov_b32_e32 v96, v12
	v_mov_b32_e32 v97, v12
	v_mov_b32_e32 v98, v12
	v_mov_b32_e32 v99, v12
	v_mov_b32_e32 v100, v12
	v_mov_b32_e32 v101, v12
	v_mov_b32_e32 v102, v12
	v_mov_b32_e32 v103, v12
	v_mov_b32_e32 v104, v12
	v_mov_b32_e32 v105, v12
	v_mov_b32_e32 v106, v12
	v_mov_b32_e32 v107, v12
	v_mov_b32_e32 v108, v12
	v_mov_b32_e32 v109, v12
	v_mov_b32_e32 v110, v12
	v_mov_b32_e32 v111, v12
	v_mov_b32_e32 v112, v12
	v_mov_b32_e32 v113, v12
	v_mov_b32_e32 v114, v12
	v_mov_b32_e32 v115, v12
	v_mov_b32_e32 v116, v12
	v_mov_b32_e32 v117, v12
	v_mov_b32_e32 v118, v12
	v_mov_b32_e32 v119, v12
	v_mov_b32_e32 v120, v12
	v_mov_b32_e32 v121, v12
	v_mov_b32_e32 v122, v12
	v_mov_b32_e32 v123, v12
	v_mov_b32_e32 v124, v12
	v_mov_b32_e32 v125, v12
	v_mov_b32_e32 v126, v12
	v_mov_b32_e32 v127, v12
	s_waitcnt vmcnt(0) lgkmcnt(0)
	s_barrier
	s_nop 0
	s_branch .LBB0_819
